# conv phase: removed a vmcnt(0) that serialized the 4th-row loads behind the first six (no outstanding load targets those registers on that path)
# baseline (speedup 1.0000x reference)
.LBB0_1130:
	s_andn2_b64 vcc, exec, s[28:29]
	s_cbranch_vccnz .LBB0_1125
	v_add_co_u32_e32 v2, vcc, 0xb000, v120
	s_nop 1
	v_addc_co_u32_e32 v3, vcc, 0, v121, vcc
	s_nop 0
	v_add_co_u32_e32 v80, vcc, 0xc000, v120
	s_nop 1
	v_addc_co_u32_e32 v81, vcc, 0, v121, vcc
	global_load_dwordx4 v[76:79], v[2:3], off
	s_nop 0
	global_load_dwordx4 v[80:83], v[80:81], off offset:1536
	s_branch .LBB0_1125
